# gemm1 k-step: vmcnt wait and first LDS stores of each half behind MFMA group 0 (as in the other GEMMs)
# speedup vs baseline: 1.0086x; 1.0008x over previous
.LBB0_180:
	v_add_u32_e32 v159, v143, v139
	v_add_u32_e32 v167, v143, v141
	v_add_u32_e32 v161, v153, v139
	v_add_u32_e32 v169, v153, v141
	v_add_u32_e32 v163, v155, v139
	v_add_u32_e32 v171, v155, v141
	s_waitcnt lgkmcnt(0)
	v_mfma_f32_32x32x16_bf16 v[48:63], v[198:201], v[202:205], v[48:63]
	s_add_i32 s21, s71, 3
	s_cmp_ge_i32 s21, s90
	v_mfma_f32_32x32x16_bf16 v[32:47], v[198:201], v[206:209], v[32:47]
	ds_read_b128 v[198:201], v159
	v_mfma_f32_32x32x16_bf16 v[16:31], v[242:245], v[202:205], v[16:31]
	ds_read_b128 v[202:205], v167 offset:16384
	v_mfma_f32_32x32x16_bf16 v[0:15], v[242:245], v[206:209], v[0:15]
	ds_read_b128 v[206:209], v167 offset:20480
	ds_read_b128 v[242:245], v159 offset:4096
	s_mov_b64 vcc, s[80:81]
	s_cbranch_vccnz .Lm1w_w0
	s_waitcnt vmcnt(8)
	s_branch .Lm1w_w1

.Lm1w_w1:
	ds_write_b128 v135, v[68:71] offset:32768
	ds_write_b128 v135, v[72:75] offset:49152
	ds_write_b128 v135, v[92:95] offset:36864
	s_waitcnt lgkmcnt(3)
	v_mfma_f32_32x32x16_bf16 v[48:63], v[198:201], v[202:205], v[48:63]
	v_mfma_f32_32x32x16_bf16 v[32:47], v[198:201], v[206:209], v[32:47]
	ds_read_b128 v[198:201], v161
	v_mfma_f32_32x32x16_bf16 v[16:31], v[242:245], v[202:205], v[16:31]
	ds_read_b128 v[202:205], v169 offset:16384
	v_mfma_f32_32x32x16_bf16 v[0:15], v[242:245], v[206:209], v[0:15]
	ds_read_b128 v[206:209], v169 offset:20480
	ds_read_b128 v[242:245], v161 offset:4096
	ds_write_b128 v135, v[84:87] offset:53248
	ds_write_b128 v135, v[108:111] offset:40960
	ds_write_b128 v135, v[100:103] offset:57344
	s_waitcnt lgkmcnt(3)
	v_mfma_f32_32x32x16_bf16 v[48:63], v[198:201], v[202:205], v[48:63]
	v_mfma_f32_32x32x16_bf16 v[32:47], v[198:201], v[206:209], v[32:47]
	ds_read_b128 v[198:201], v163
	v_mfma_f32_32x32x16_bf16 v[16:31], v[242:245], v[202:205], v[16:31]
	ds_read_b128 v[202:205], v171 offset:16384
	v_mfma_f32_32x32x16_bf16 v[0:15], v[242:245], v[206:209], v[0:15]
	ds_read_b128 v[206:209], v171 offset:20480
	ds_read_b128 v[242:245], v163 offset:4096
	ds_write_b128 v135, v[124:127] offset:45056
	ds_write_b128 v135, v[116:119] offset:61440
	s_waitcnt lgkmcnt(2)
	v_mfma_f32_32x32x16_bf16 v[48:63], v[198:201], v[202:205], v[48:63]
	v_mfma_f32_32x32x16_bf16 v[32:47], v[198:201], v[206:209], v[32:47]
	v_mfma_f32_32x32x16_bf16 v[16:31], v[242:245], v[202:205], v[16:31]
	v_mfma_f32_32x32x16_bf16 v[0:15], v[242:245], v[206:209], v[0:15]
	s_waitcnt lgkmcnt(0)
	s_barrier
	ds_read_b128 v[198:201], v157 offset:32768
	ds_read_b128 v[202:205], v165 offset:49152
	ds_read_b128 v[206:209], v165 offset:53248
	ds_read_b128 v[242:245], v157 offset:36864
	s_cbranch_scc1 .LBB0_184
	s_add_i32 s21, s15, 64
	s_add_i32 s74, s15, 0x840
	s_cmp_lt_u32 s71, 13
	s_cselect_b64 s[84:85], -1, 0
	s_and_b64 vcc, s[84:85], exec
	s_cselect_b32 vcc_lo, s74, s21
	v_mov_b32_e32 v81, v80
	s_ashr_i32 vcc_hi, vcc_lo, 31
	v_mov_b32_e32 v82, v80
	v_mov_b32_e32 v83, v80
	v_mov_b64_e32 v[68:69], v[80:81]
	v_lshl_add_u64 v[116:117], vcc, 1, v[178:179]
	s_or_b64 vcc, s[84:85], s[4:5]
	v_mov_b64_e32 v[70:71], v[82:83]
	s_and_saveexec_b64 s[84:85], vcc
	s_cbranch_execz .LBB0_183
	global_load_dwordx4 v[68:71], v[116:117], off

.LBB0_184:
	s_waitcnt lgkmcnt(0)
	v_mfma_f32_32x32x16_bf16 v[48:63], v[198:201], v[202:205], v[48:63]
	v_mfma_f32_32x32x16_bf16 v[32:47], v[198:201], v[206:209], v[32:47]
	ds_read_b128 v[198:201], v159 offset:32768
	v_mfma_f32_32x32x16_bf16 v[16:31], v[242:245], v[202:205], v[16:31]
	ds_read_b128 v[202:205], v167 offset:49152
	v_mfma_f32_32x32x16_bf16 v[0:15], v[242:245], v[206:209], v[0:15]
	ds_read_b128 v[206:209], v167 offset:53248
	ds_read_b128 v[242:245], v159 offset:36864
	s_waitcnt vmcnt(8)
	ds_write_b128 v135, v[64:67]
	ds_write_b128 v135, v[76:79] offset:16384
	ds_write_b128 v135, v[96:99] offset:4096
	s_waitcnt lgkmcnt(3)
	v_mfma_f32_32x32x16_bf16 v[48:63], v[198:201], v[202:205], v[48:63]
	v_mfma_f32_32x32x16_bf16 v[32:47], v[198:201], v[206:209], v[32:47]
	ds_read_b128 v[198:201], v161 offset:32768
	v_mfma_f32_32x32x16_bf16 v[16:31], v[242:245], v[202:205], v[16:31]
	ds_read_b128 v[202:205], v169 offset:49152
	v_mfma_f32_32x32x16_bf16 v[0:15], v[242:245], v[206:209], v[0:15]
	ds_read_b128 v[206:209], v169 offset:53248
	ds_read_b128 v[242:245], v161 offset:36864
	ds_write_b128 v135, v[88:91] offset:20480
	ds_write_b128 v135, v[112:115] offset:8192
	ds_write_b128 v135, v[104:107] offset:24576
	s_waitcnt lgkmcnt(3)
	v_mfma_f32_32x32x16_bf16 v[48:63], v[198:201], v[202:205], v[48:63]
	v_mfma_f32_32x32x16_bf16 v[32:47], v[198:201], v[206:209], v[32:47]
	ds_read_b128 v[198:201], v163 offset:32768
	v_mfma_f32_32x32x16_bf16 v[16:31], v[242:245], v[202:205], v[16:31]
	ds_read_b128 v[202:205], v171 offset:49152
	v_mfma_f32_32x32x16_bf16 v[0:15], v[242:245], v[206:209], v[0:15]
	ds_read_b128 v[206:209], v171 offset:53248
	ds_read_b128 v[242:245], v163 offset:36864
	ds_write_b128 v135, v[128:131] offset:12288
	ds_write_b128 v135, v[120:123] offset:28672
	s_waitcnt lgkmcnt(2)
	v_mfma_f32_32x32x16_bf16 v[48:63], v[198:201], v[202:205], v[48:63]
	v_mfma_f32_32x32x16_bf16 v[32:47], v[198:201], v[206:209], v[32:47]
	v_mfma_f32_32x32x16_bf16 v[16:31], v[242:245], v[202:205], v[16:31]
	v_mfma_f32_32x32x16_bf16 v[0:15], v[242:245], v[206:209], v[0:15]
